# v19 plus post phase: gate (z) loads issued together with the row's first loads
# speedup vs baseline: 1.0086x; 1.0031x over previous
; DI float bflo(unsigned w) { return __uint_as_float(w << 16); }
; DI float bfhi(unsigned w) { return __uint_as_float(w & 0xffff0000u); }
; DI float shx(float v, int m) { const int lane = tid_() & 63; return __builtin_bit_cast(float, __builtin_amdgcn_ds_bpermute((lane ^ m) << 2, __builtin_bit_cast(int, v))); }
; DI float sigmoidf_(float x) { return 1.f / (1.f + __expf(-x)); }
; DI void phase_post(const Params& p, int L) {
;     ...
;         if (isa) { const u32x4 a = *(const u32x4*)(pr + 1024 + 16 * lane), bq = *(const u32x4*)(pr + 1024 + 16 * lane + 8);
;             const unsigned uw[8] = {a.x, a.y, a.z, a.w, bq.x, bq.y, bq.z, bq.w};
;             for (int q = 0; q < 8; ++q) { o[2 * q] = bflo(uw[q]); o[2 * q + 1] = bfhi(uw[q]); } }
;         else { const int l2 = lane - 32;
;             const u32x4 a = *(const u32x4*)(pr + 16 * l2), bq = *(const u32x4*)(pr + 16 * l2 + 8), c = *(const u32x4*)(pr + 512 + 16 * l2), d = *(const u32x4*)(pr + 512 + 16 * l2 + 8);
;             const unsigned u1[8] = {a.x, a.y, a.z, a.w, bq.x, bq.y, bq.z, bq.w}, u2[8] = {c.x, c.y, c.z, c.w, d.x, d.y, d.z, d.w};
;             for (int q = 0; q < 8; ++q) { o[2 * q] = bflo(u1[q]) - lam * bflo(u2[q]); o[2 * q + 1] = bfhi(u1[q]) - lam * bfhi(u2[q]); } }
;         float ss = 0.f; for (int e = 0; e < 16; ++e) ss += o[e] * o[e];
;         ss += shx(ss, 1); ss += shx(ss, 2); ss += shx(ss, 4);
;         const float rn = rsqrtf(ss * (1.f / 128.f) + EPS);
;         float g[16];
;         if (isa) { const u32x4 a = *(const u32x4*)(pr + 1536 + 16 * lane), bq = *(const u32x4*)(pr + 1536 + 16 * lane + 8);
;             const unsigned uw[8] = {a.x, a.y, a.z, a.w, bq.x, bq.y, bq.z, bq.w};
;             for (int q = 0; q < 8; ++q) { const float z0 = bflo(uw[q]), z1 = bfhi(uw[q]); g[2 * q] = z0 * sigmoidf_(z0); g[2 * q + 1] = z1 * sigmoidf_(z1); } }
;         else for (int e = 0; e < 16; ++e) g[e] = 1.f;
;         for (int e = 0; e < 16; ++e) o[e] = o[e] * rn * nw[e] * g[e];
.LBB0_615:
	s_andn2_saveexec_b64 s[2:3], s[2:3]
	s_cbranch_execz .LBB0_617
	v_lshlrev_b32_e32 v0, 1, v30
	v_lshl_add_u64 v[8:9], v[2:3], 0, v[0:1]
	global_load_dwordx4 v[4:7], v[8:9], off offset:2048
	global_load_dwordx4 v[48:51], v[8:9], off offset:2064
	global_load_dwordx4 v[88:91], v[8:9], off offset:3088
	global_load_dwordx4 v[92:95], v[8:9], off offset:3072
	s_waitcnt vmcnt(3)
	v_lshlrev_b32_e32 v36, 16, v4
	v_and_b32_e32 v37, 0xffff0000, v4
	v_lshlrev_b32_e32 v38, 16, v5
	v_and_b32_e32 v39, 0xffff0000, v5
	v_lshlrev_b32_e32 v40, 16, v6
	v_and_b32_e32 v41, 0xffff0000, v6
	v_lshlrev_b32_e32 v42, 16, v7
	v_and_b32_e32 v43, 0xffff0000, v7
	s_waitcnt vmcnt(2)
	v_lshlrev_b32_e32 v44, 16, v48
	v_and_b32_e32 v45, 0xffff0000, v48
	v_lshlrev_b32_e32 v46, 16, v49
	v_and_b32_e32 v47, 0xffff0000, v49
	v_lshlrev_b32_e32 v48, 16, v50
	v_and_b32_e32 v49, 0xffff0000, v50
	v_lshlrev_b32_e32 v50, 16, v51
	v_and_b32_e32 v51, 0xffff0000, v51
.LBB0_617:
	s_or_b64 exec, exec, s[2:3]
	v_mul_f32_e32 v0, v37, v37
	v_fmac_f32_e32 v0, v36, v36
	v_fmac_f32_e32 v0, v38, v38
	v_fmac_f32_e32 v0, v39, v39
	v_fmac_f32_e32 v0, v40, v40
	v_fmac_f32_e32 v0, v41, v41
	v_fmac_f32_e32 v0, v42, v42
	v_fmac_f32_e32 v0, v43, v43
	v_pk_mul_f32 v[52:53], v[44:45], v[44:45]
	v_pk_mul_f32 v[8:9], v[46:47], v[46:47]
	v_add_f32_e32 v0, v52, v0
	v_add_f32_e32 v0, v53, v0
	v_add_f32_e32 v0, v8, v0
	v_pk_mul_f32 v[6:7], v[48:49], v[48:49]
	v_add_f32_e32 v0, v9, v0
	v_add_f32_e32 v0, v6, v0
	v_pk_mul_f32 v[4:5], v[50:51], v[50:51]
	v_add_f32_e32 v0, v7, v0
	v_add_f32_e32 v0, v4, v0
	v_mov_b32_e32 v4, v194
	v_add_f32_e32 v0, v5, v0
	v_lshlrev_b32_e32 v4, 2, v4
	v_bitop3_b32 v4, v4, 4, v199 bitop3:0x6c
	ds_bpermute_b32 v4, v4, v0
	v_mov_b32_e32 v62, 1.0
	v_mov_b32_e32 v63, 1.0
	v_mov_b32_e32 v8, 1.0
	v_mov_b32_e32 v9, 1.0
	s_waitcnt lgkmcnt(0)
	v_add_f32_e32 v0, v0, v4
	v_mov_b32_e32 v4, v194
	v_mov_b32_e32 v54, 1.0
	v_lshlrev_b32_e32 v4, 2, v4
	v_bitop3_b32 v4, v4, 8, v199 bitop3:0x6c
	ds_bpermute_b32 v4, v4, v0
	v_mov_b32_e32 v55, 1.0
	v_mov_b32_e32 v6, 1.0
	v_mov_b32_e32 v7, 1.0
	v_mov_b32_e32 v56, 1.0
	s_waitcnt lgkmcnt(0)
	v_add_f32_e32 v11, v0, v4
	v_mov_b32_e32 v0, v194
	v_mov_b32_e32 v57, 1.0
	v_lshlrev_b32_e32 v0, 2, v0
	v_bitop3_b32 v0, v0, 16, v199 bitop3:0x6c
	ds_bpermute_b32 v31, v0, v11
	v_mov_b32_e32 v58, 1.0
	v_mov_b32_e32 v59, 1.0
	v_mov_b32_e32 v60, 1.0
	v_mov_b32_e32 v61, 1.0
	v_mov_b32_e32 v4, 1.0
	v_mov_b32_e32 v5, 1.0
	s_and_saveexec_b64 s[44:45], s[40:41]
	s_cbranch_execz .LBB0_612
	v_lshlrev_b32_e32 v0, 1, v30
	v_lshl_add_u64 v[6:7], v[2:3], 0, v[0:1]
	s_waitcnt vmcnt(0)
	v_mov_b32_e32 v2, v88
	v_mov_b32_e32 v3, v89
	v_mov_b32_e32 v4, v90
	v_mov_b32_e32 v5, v91
	v_mov_b32_e32 v6, v92
	v_mov_b32_e32 v7, v93
	v_mov_b32_e32 v8, v94
	v_mov_b32_e32 v9, v95
	v_lshlrev_b32_e32 v53, 16, v6
	v_and_b32_e32 v52, 0xffff0000, v6
	v_mul_f32_e32 v0, 0xbfb8aa3b, v53
	v_exp_f32_e32 v55, v0
	v_mul_f32_e32 v0, 0xbfb8aa3b, v52
	v_exp_f32_e32 v54, v0
	s_nop 0
	v_pk_add_f32 v[54:55], v[54:55], 1.0 op_sel_hi:[1,0]
	s_nop 0
	v_div_scale_f32 v0, s[2:3], v55, v55, 1.0
	v_rcp_f32_e32 v6, v0
	s_nop 0
	v_fma_f32 v56, -v0, v6, 1.0
	v_fmac_f32_e32 v6, v56, v6
	v_div_scale_f32 v56, vcc, 1.0, v55, 1.0
	v_mul_f32_e32 v57, v56, v6
	v_fma_f32 v58, -v0, v57, v56
	v_fmac_f32_e32 v57, v58, v6
	v_fma_f32 v0, -v0, v57, v56
	v_div_fmas_f32 v0, v0, v6, v57
	v_div_fixup_f32 v55, v0, v55, 1.0
	v_div_scale_f32 v0, s[2:3], v54, v54, 1.0
	v_rcp_f32_e32 v6, v0
	s_nop 0
	v_fma_f32 v56, -v0, v6, 1.0
	v_fmac_f32_e32 v6, v56, v6
	v_div_scale_f32 v56, vcc, 1.0, v54, 1.0
	v_mul_f32_e32 v57, v56, v6
	v_fma_f32 v58, -v0, v57, v56
	v_fmac_f32_e32 v57, v58, v6
	v_fma_f32 v0, -v0, v57, v56
	v_div_fmas_f32 v0, v0, v6, v57
	v_and_b32_e32 v6, 0xffff0000, v7
	v_lshlrev_b32_e32 v7, 16, v7
	v_div_fixup_f32 v54, v0, v54, 1.0
	v_mul_f32_e32 v0, 0xbfb8aa3b, v7
	v_pk_mul_f32 v[52:53], v[54:55], v[52:53]
	v_exp_f32_e32 v55, v0
	v_mul_f32_e32 v0, 0xbfb8aa3b, v6
	v_exp_f32_e32 v54, v0
	s_nop 0
	v_pk_add_f32 v[54:55], v[54:55], 1.0 op_sel_hi:[1,0]
	s_nop 0
	v_div_scale_f32 v0, s[2:3], v55, v55, 1.0
	v_rcp_f32_e32 v56, v0
	s_nop 0
	v_fma_f32 v57, -v0, v56, 1.0
	v_fmac_f32_e32 v56, v57, v56
	v_div_scale_f32 v57, vcc, 1.0, v55, 1.0
	v_mul_f32_e32 v58, v57, v56
	v_fma_f32 v59, -v0, v58, v57
	v_fmac_f32_e32 v58, v59, v56
	v_fma_f32 v0, -v0, v58, v57
	v_div_fmas_f32 v0, v0, v56, v58
	v_div_fixup_f32 v55, v0, v55, 1.0
	v_div_scale_f32 v0, s[2:3], v54, v54, 1.0
	v_rcp_f32_e32 v56, v0
	s_nop 0
	v_fma_f32 v57, -v0, v56, 1.0
	v_fmac_f32_e32 v56, v57, v56
	v_div_scale_f32 v57, vcc, 1.0, v54, 1.0
	v_mul_f32_e32 v58, v57, v56
	v_fma_f32 v59, -v0, v58, v57
	v_fmac_f32_e32 v58, v59, v56
	v_fma_f32 v0, -v0, v58, v57
	v_div_fmas_f32 v0, v0, v56, v58
	v_div_fixup_f32 v54, v0, v54, 1.0
	v_pk_mul_f32 v[6:7], v[54:55], v[6:7]
	v_lshlrev_b32_e32 v55, 16, v8
	v_and_b32_e32 v54, 0xffff0000, v8
	v_mul_f32_e32 v0, 0xbfb8aa3b, v55
	v_exp_f32_e32 v57, v0
	v_mul_f32_e32 v0, 0xbfb8aa3b, v54
	v_exp_f32_e32 v56, v0
	s_nop 0
	v_pk_add_f32 v[56:57], v[56:57], 1.0 op_sel_hi:[1,0]
	s_nop 0
	v_div_scale_f32 v0, s[2:3], v57, v57, 1.0
	v_rcp_f32_e32 v8, v0
	s_nop 0
	v_fma_f32 v58, -v0, v8, 1.0
	v_fmac_f32_e32 v8, v58, v8
	v_div_scale_f32 v58, vcc, 1.0, v57, 1.0
	v_mul_f32_e32 v59, v58, v8
	v_fma_f32 v60, -v0, v59, v58
	v_fmac_f32_e32 v59, v60, v8
	v_fma_f32 v0, -v0, v59, v58
	v_div_fmas_f32 v0, v0, v8, v59
	v_div_fixup_f32 v57, v0, v57, 1.0
	v_div_scale_f32 v0, s[2:3], v56, v56, 1.0
	v_rcp_f32_e32 v8, v0
	s_nop 0
	v_fma_f32 v58, -v0, v8, 1.0
; DI float bflo(unsigned w) { return __uint_as_float(w << 16); }
; DI float bfhi(unsigned w) { return __uint_as_float(w & 0xffff0000u); }
; DI float sigmoidf_(float x) { return 1.f / (1.f + __expf(-x)); }
; DI void phase_post(const Params& p, int L) {
;     ...
;         if (isa) { const u32x4 a = *(const u32x4*)(pr + 1536 + 16 * lane), bq = *(const u32x4*)(pr + 1536 + 16 * lane + 8);
;             const unsigned uw[8] = {a.x, a.y, a.z, a.w, bq.x, bq.y, bq.z, bq.w};
;             for (int q = 0; q < 8; ++q) { const float z0 = bflo(uw[q]), z1 = bfhi(uw[q]); g[2 * q] = z0 * sigmoidf_(z0); g[2 * q + 1] = z1 * sigmoidf_(z1); } }
;         else for (int e = 0; e < 16; ++e) g[e] = 1.f;
;         for (int e = 0; e < 16; ++e) o[e] = o[e] * rn * nw[e] * g[e];
	v_fmac_f32_e32 v8, v58, v8
	v_div_scale_f32 v58, vcc, 1.0, v56, 1.0
	v_mul_f32_e32 v59, v58, v8
	v_fma_f32 v60, -v0, v59, v58
	v_fmac_f32_e32 v59, v60, v8
	v_fma_f32 v0, -v0, v59, v58
	v_div_fmas_f32 v0, v0, v8, v59
	v_and_b32_e32 v8, 0xffff0000, v9
	v_lshlrev_b32_e32 v9, 16, v9
	v_div_fixup_f32 v56, v0, v56, 1.0
	v_mul_f32_e32 v0, 0xbfb8aa3b, v9
	v_pk_mul_f32 v[54:55], v[56:57], v[54:55]
	v_exp_f32_e32 v57, v0
	v_mul_f32_e32 v0, 0xbfb8aa3b, v8
	v_exp_f32_e32 v56, v0
	s_nop 0
	v_pk_add_f32 v[56:57], v[56:57], 1.0 op_sel_hi:[1,0]
	s_nop 0
	v_div_scale_f32 v0, s[2:3], v57, v57, 1.0
	v_rcp_f32_e32 v58, v0
	s_nop 0
	v_fma_f32 v59, -v0, v58, 1.0
	v_fmac_f32_e32 v58, v59, v58
	v_div_scale_f32 v59, vcc, 1.0, v57, 1.0
	v_mul_f32_e32 v60, v59, v58
	v_fma_f32 v61, -v0, v60, v59
	v_fmac_f32_e32 v60, v61, v58
	v_fma_f32 v0, -v0, v60, v59
	v_div_fmas_f32 v0, v0, v58, v60
	v_div_fixup_f32 v57, v0, v57, 1.0
	v_div_scale_f32 v0, s[2:3], v56, v56, 1.0
	v_rcp_f32_e32 v58, v0
	s_nop 0
	v_fma_f32 v59, -v0, v58, 1.0
	v_fmac_f32_e32 v58, v59, v58
	v_div_scale_f32 v59, vcc, 1.0, v56, 1.0
	v_mul_f32_e32 v60, v59, v58
	v_fma_f32 v61, -v0, v60, v59
	v_fmac_f32_e32 v60, v61, v58
	v_fma_f32 v0, -v0, v60, v59
	v_div_fmas_f32 v0, v0, v58, v60
	v_div_fixup_f32 v56, v0, v56, 1.0
	v_pk_mul_f32 v[8:9], v[56:57], v[8:9]
	v_lshlrev_b32_e32 v56, 16, v2
	v_and_b32_e32 v57, 0xffff0000, v2
	v_mul_f32_e32 v0, 0xbfb8aa3b, v56
	v_exp_f32_e32 v58, v0
	v_mul_f32_e32 v0, 0xbfb8aa3b, v57
	v_exp_f32_e32 v59, v0
	s_nop 0
	v_pk_add_f32 v[58:59], v[58:59], 1.0 op_sel_hi:[1,0]
	s_nop 0
	v_div_scale_f32 v0, s[2:3], v59, v59, 1.0
	v_rcp_f32_e32 v2, v0
	s_nop 0
	v_fma_f32 v60, -v0, v2, 1.0
	v_fmac_f32_e32 v2, v60, v2
	v_div_scale_f32 v60, vcc, 1.0, v59, 1.0
	v_mul_f32_e32 v61, v60, v2
	v_fma_f32 v62, -v0, v61, v60
	v_fmac_f32_e32 v61, v62, v2
	v_fma_f32 v0, -v0, v61, v60
	v_div_fmas_f32 v0, v0, v2, v61
	v_div_fixup_f32 v59, v0, v59, 1.0
	v_div_scale_f32 v0, s[2:3], v58, v58, 1.0
	v_rcp_f32_e32 v2, v0
	s_nop 0
	v_fma_f32 v60, -v0, v2, 1.0
	v_fmac_f32_e32 v2, v60, v2
	v_div_scale_f32 v60, vcc, 1.0, v58, 1.0
	v_mul_f32_e32 v61, v60, v2
	v_fma_f32 v62, -v0, v61, v60
	v_fmac_f32_e32 v61, v62, v2
	v_fma_f32 v0, -v0, v61, v60
	v_div_fmas_f32 v0, v0, v2, v61
	v_lshlrev_b32_e32 v2, 16, v3
	v_div_fixup_f32 v58, v0, v58, 1.0
	v_and_b32_e32 v3, 0xffff0000, v3
	v_mul_f32_e32 v0, 0xbfb8aa3b, v2
	v_pk_mul_f32 v[56:57], v[58:59], v[56:57]
	v_exp_f32_e32 v58, v0
	v_mul_f32_e32 v0, 0xbfb8aa3b, v3
	v_exp_f32_e32 v59, v0
	s_nop 0
	v_pk_add_f32 v[58:59], v[58:59], 1.0 op_sel_hi:[1,0]
	s_nop 0
	v_div_scale_f32 v0, s[2:3], v59, v59, 1.0
	v_rcp_f32_e32 v60, v0
	s_nop 0
	v_fma_f32 v61, -v0, v60, 1.0
	v_fmac_f32_e32 v60, v61, v60
	v_div_scale_f32 v61, vcc, 1.0, v59, 1.0
	v_mul_f32_e32 v62, v61, v60
	v_fma_f32 v63, -v0, v62, v61
	v_fmac_f32_e32 v62, v63, v60
	v_fma_f32 v0, -v0, v62, v61
	v_div_fmas_f32 v0, v0, v60, v62
	v_div_fixup_f32 v59, v0, v59, 1.0
	v_div_scale_f32 v0, s[2:3], v58, v58, 1.0
	v_rcp_f32_e32 v60, v0
	s_nop 0
	v_fma_f32 v61, -v0, v60, 1.0
	v_fmac_f32_e32 v60, v61, v60
	v_div_scale_f32 v61, vcc, 1.0, v58, 1.0
	v_mul_f32_e32 v62, v61, v60
	v_fma_f32 v63, -v0, v62, v61
	v_fmac_f32_e32 v62, v63, v60
	v_fma_f32 v0, -v0, v62, v61
	v_div_fmas_f32 v0, v0, v60, v62
	v_div_fixup_f32 v58, v0, v58, 1.0
	v_pk_mul_f32 v[58:59], v[58:59], v[2:3]
	v_lshlrev_b32_e32 v2, 16, v4
	v_and_b32_e32 v3, 0xffff0000, v4
	v_mul_f32_e32 v0, 0xbfb8aa3b, v2
	v_exp_f32_e32 v60, v0
	v_mul_f32_e32 v0, 0xbfb8aa3b, v3
	v_exp_f32_e32 v61, v0
	s_nop 0
	v_pk_add_f32 v[60:61], v[60:61], 1.0 op_sel_hi:[1,0]
	s_nop 0
	v_div_scale_f32 v0, s[2:3], v61, v61, 1.0
	v_rcp_f32_e32 v4, v0
	s_nop 0
	v_fma_f32 v62, -v0, v4, 1.0
	v_fmac_f32_e32 v4, v62, v4
	v_div_scale_f32 v62, vcc, 1.0, v61, 1.0
	v_mul_f32_e32 v63, v62, v4
	v_fma_f32 v64, -v0, v63, v62
	v_fmac_f32_e32 v63, v64, v4
	v_fma_f32 v0, -v0, v63, v62
	v_div_fmas_f32 v0, v0, v4, v63
	v_div_fixup_f32 v61, v0, v61, 1.0
	v_div_scale_f32 v0, s[2:3], v60, v60, 1.0
	v_rcp_f32_e32 v4, v0
	s_nop 0
	v_fma_f32 v62, -v0, v4, 1.0
	v_fmac_f32_e32 v4, v62, v4
	v_div_scale_f32 v62, vcc, 1.0, v60, 1.0
	v_mul_f32_e32 v63, v62, v4
	v_fma_f32 v64, -v0, v63, v62
	v_fmac_f32_e32 v63, v64, v4
	v_fma_f32 v0, -v0, v63, v62
	v_div_fmas_f32 v0, v0, v4, v63
	v_div_fixup_f32 v60, v0, v60, 1.0
	v_pk_mul_f32 v[60:61], v[60:61], v[2:3]
	v_lshlrev_b32_e32 v2, 16, v5
	v_and_b32_e32 v3, 0xffff0000, v5
	v_mul_f32_e32 v0, 0xbfb8aa3b, v2
	v_exp_f32_e32 v4, v0
	v_mul_f32_e32 v0, 0xbfb8aa3b, v3
	v_exp_f32_e32 v5, v0
	s_nop 0
	v_pk_add_f32 v[4:5], v[4:5], 1.0 op_sel_hi:[1,0]
	s_nop 0
	v_div_scale_f32 v0, s[2:3], v5, v5, 1.0
	v_rcp_f32_e32 v62, v0
	s_nop 0
	v_fma_f32 v63, -v0, v62, 1.0
	v_fmac_f32_e32 v62, v63, v62
	v_div_scale_f32 v63, vcc, 1.0, v5, 1.0
	v_mul_f32_e32 v64, v63, v62
	v_fma_f32 v65, -v0, v64, v63
	v_fmac_f32_e32 v64, v65, v62
	v_fma_f32 v0, -v0, v64, v63
	v_div_fmas_f32 v0, v0, v62, v64
	v_div_fixup_f32 v5, v0, v5, 1.0
	v_div_scale_f32 v0, s[2:3], v4, v4, 1.0
	v_rcp_f32_e32 v62, v0
	s_nop 0
	v_fma_f32 v63, -v0, v62, 1.0
	v_fmac_f32_e32 v62, v63, v62
	v_div_scale_f32 v63, vcc, 1.0, v4, 1.0
	v_mul_f32_e32 v64, v63, v62
	v_fma_f32 v65, -v0, v64, v63
	v_fmac_f32_e32 v64, v65, v62
	v_fma_f32 v0, -v0, v64, v63
	v_div_fmas_f32 v0, v0, v62, v64
	v_div_fixup_f32 v4, v0, v4, 1.0
	v_pk_mul_f32 v[4:5], v[4:5], v[2:3]
	v_mov_b32_e32 v62, v9
	v_mov_b32_e32 v63, v8
	v_mov_b32_e32 v8, v55
	v_mov_b32_e32 v9, v54
	v_mov_b32_e32 v54, v7
	v_mov_b32_e32 v55, v6
	v_mov_b32_e32 v6, v53
	v_mov_b32_e32 v7, v52
	s_branch .LBB0_612
